# v37 plus DPP quad/row-mirror reductions instead of ds_bpermute in the sample-attention key loop
# speedup vs baseline: 1.0057x; 1.0019x over previous
; __device__ __forceinline__ void attn_sample_g12(const Args& a, LAS unsigned char* lds, const bf16* Q, const bf16* Kb, const bf16* Vb, bf16* OG, float* ML, int b, int g, int tid) {
;     ...
;         for (int jj = 0; jj < 16; ++jj) { float t = (kk[jj][0] * q[0] + kk[jj][1] * q[1]) + (kk[jj][2] * q[2] + kk[jj][3] * q[3]);
;             t += __shfl_xor(t, 1); t += __shfl_xor(t, 2); t += __shfl_xor(t, 4); t += __shfl_xor(t, 8);
;             sc[jj] = (j0 + jj < jend) ? t : -INFINITY; cm = fmaxf(cm, sc[jj]); }
.LBB0_1022:
	s_or_b64 exec, exec, s[46:47]
	s_waitcnt vmcnt(1)
	v_mov_b32_e32 v178, v35
	v_mov_b32_e32 v35, v37
	v_mov_b32_e32 v179, v36
	v_pk_mul_f32 v[34:35], v[34:35], v[146:147]
	s_nop 0
	v_pk_fma_f32 v[34:35], v[178:179], v[148:149], v[34:35]
	s_nop 0
	v_add_f32_e32 v36, v34, v35
	s_nop 1
	v_mov_b32_dpp v37, v36 quad_perm:[1,0,3,2] row_mask:0xf bank_mask:0xf
	v_mov_b32_e32 v34, v43
	v_mov_b32_e32 v43, v45
	v_mov_b32_e32 v35, v44
	s_waitcnt lgkmcnt(0)
	v_add_f32_e32 v44, v36, v37
	v_pk_mul_f32 v[36:37], v[42:43], v[146:147]
	s_nop 1
	v_mov_b32_dpp v177, v44 quad_perm:[2,3,0,1] row_mask:0xf bank_mask:0xf
	v_pk_fma_f32 v[34:35], v[34:35], v[148:149], v[36:37]
	s_waitcnt lgkmcnt(0)
	v_add_f32_e32 v36, v44, v177
	v_add_f32_e32 v34, v34, v35
	s_nop 1
	v_mov_b32_dpp v35, v34 quad_perm:[1,0,3,2] row_mask:0xf bank_mask:0xf
	s_nop 1
	v_mov_b32_dpp v37, v36 row_half_mirror row_mask:0xf bank_mask:0xf
	s_waitcnt lgkmcnt(1)
	v_add_f32_e32 v34, v34, v35
	s_nop 1
	v_mov_b32_dpp v35, v34 quad_perm:[2,3,0,1] row_mask:0xf bank_mask:0xf
	s_waitcnt lgkmcnt(1)
	v_add_f32_e32 v43, v36, v37
	s_nop 1
	v_mov_b32_dpp v44, v43 row_mirror row_mask:0xf bank_mask:0xf
	s_waitcnt lgkmcnt(1)
	v_add_f32_e32 v42, v34, v35
	v_mov_b32_e32 v34, v51
	v_mov_b32_e32 v51, v53
	v_mov_b32_e32 v35, v52
	v_pk_mul_f32 v[36:37], v[50:51], v[146:147]
	s_nop 1
	v_mov_b32_dpp v45, v42 row_half_mirror row_mask:0xf bank_mask:0xf
	v_pk_fma_f32 v[34:35], v[34:35], v[148:149], v[36:37]
	s_waitcnt lgkmcnt(1)
	v_add_f32_e32 v43, v43, v44
	v_add_f32_e32 v34, v34, v35
	s_nop 1
	v_mov_b32_dpp v35, v34 quad_perm:[1,0,3,2] row_mask:0xf bank_mask:0xf
	s_waitcnt lgkmcnt(1)
	v_add_f32_e32 v42, v42, v45
	s_nop 1
	v_mov_b32_dpp v45, v42 row_mirror row_mask:0xf bank_mask:0xf
	v_max_f32_e32 v44, 0xff800000, v43
	s_waitcnt lgkmcnt(1)
	v_add_f32_e32 v50, v34, v35
	v_mov_b32_e32 v34, v55
	v_mov_b32_e32 v55, v57
	v_mov_b32_e32 v35, v56
	v_pk_mul_f32 v[36:37], v[54:55], v[146:147]
	s_nop 1
	v_mov_b32_dpp v51, v50 quad_perm:[2,3,0,1] row_mask:0xf bank_mask:0xf
	v_pk_fma_f32 v[34:35], v[34:35], v[148:149], v[36:37]
	s_waitcnt lgkmcnt(1)
	v_add_f32_e32 v36, v42, v45
	v_add_f32_e32 v34, v34, v35
	s_nop 1
	v_mov_b32_dpp v35, v34 quad_perm:[1,0,3,2] row_mask:0xf bank_mask:0xf
	s_waitcnt lgkmcnt(1)
	v_add_f32_e32 v42, v50, v51
	v_cndmask_b32_e32 v45, v169, v36, vcc
	s_nop 1
	v_mov_b32_dpp v50, v42 row_half_mirror row_mask:0xf bank_mask:0xf
	s_waitcnt vmcnt(0)
	v_mov_b32_e32 v55, v8
	s_waitcnt lgkmcnt(1)
	v_add_f32_e32 v51, v34, v35
	v_mov_b32_e32 v34, v63
	v_mov_b32_e32 v63, v65
	v_mov_b32_e32 v35, v64
	v_pk_mul_f32 v[36:37], v[62:63], v[146:147]
	s_nop 1
	v_mov_b32_dpp v52, v51 quad_perm:[2,3,0,1] row_mask:0xf bank_mask:0xf
	v_pk_fma_f32 v[34:35], v[34:35], v[148:149], v[36:37]
	s_waitcnt lgkmcnt(1)
	v_add_f32_e32 v36, v42, v50
	v_add_f32_e32 v34, v34, v35
	s_nop 1
	v_mov_b32_dpp v35, v34 quad_perm:[1,0,3,2] row_mask:0xf bank_mask:0xf
	s_nop 1
	v_mov_b32_dpp v37, v36 row_mirror row_mask:0xf bank_mask:0xf
	s_waitcnt lgkmcnt(2)
	v_add_f32_e32 v42, v51, v52
	s_nop 1
	v_mov_b32_dpp v50, v42 row_half_mirror row_mask:0xf bank_mask:0xf
	v_mov_b32_e32 v8, v7
	s_waitcnt lgkmcnt(2)
	v_add_f32_e32 v34, v34, v35
	s_nop 1
	v_mov_b32_dpp v35, v34 quad_perm:[2,3,0,1] row_mask:0xf bank_mask:0xf
	s_waitcnt lgkmcnt(2)
	v_add_f32_e32 v36, v36, v37
	v_cndmask_b32_e64 v51, v169, v36, s[16:17]
	s_waitcnt lgkmcnt(1)
	v_add_f32_e32 v42, v42, v50
	s_nop 1
	v_mov_b32_dpp v50, v42 row_mirror row_mask:0xf bank_mask:0xf
	s_waitcnt lgkmcnt(1)
	v_add_f32_e32 v52, v34, v35
	v_mov_b32_e32 v34, v71
	v_mov_b32_e32 v71, v73
	v_mov_b32_e32 v35, v72
	v_pk_mul_f32 v[36:37], v[70:71], v[146:147]
	s_nop 1
	v_mov_b32_dpp v53, v52 row_half_mirror row_mask:0xf bank_mask:0xf
	v_pk_fma_f32 v[34:35], v[34:35], v[148:149], v[36:37]
	s_waitcnt lgkmcnt(1)
	v_add_f32_e32 v42, v42, v50
	v_add_f32_e32 v34, v34, v35
	s_nop 1
	v_mov_b32_dpp v35, v34 quad_perm:[1,0,3,2] row_mask:0xf bank_mask:0xf
	s_waitcnt lgkmcnt(1)
	v_add_f32_e32 v50, v52, v53
	s_nop 1
	v_mov_b32_dpp v52, v50 row_mirror row_mask:0xf bank_mask:0xf
	v_cndmask_b32_e64 v56, v169, v42, s[18:19]
	v_max3_f32 v44, v44, v45, v51
	s_waitcnt lgkmcnt(1)
	v_add_f32_e32 v53, v34, v35
	v_mov_b32_e32 v34, v79
	v_mov_b32_e32 v79, v81
	v_mov_b32_e32 v35, v80
	v_pk_mul_f32 v[36:37], v[78:79], v[146:147]
	s_nop 1
	v_mov_b32_dpp v54, v53 quad_perm:[2,3,0,1] row_mask:0xf bank_mask:0xf
	v_pk_fma_f32 v[34:35], v[34:35], v[148:149], v[36:37]
	s_waitcnt lgkmcnt(1)
	v_add_f32_e32 v36, v50, v52
	v_add_f32_e32 v34, v34, v35
	s_nop 1
	v_mov_b32_dpp v35, v34 quad_perm:[1,0,3,2] row_mask:0xf bank_mask:0xf
	s_waitcnt lgkmcnt(1)
	v_add_f32_e32 v37, v53, v54
	s_nop 1
	v_mov_b32_dpp v42, v37 row_half_mirror row_mask:0xf bank_mask:0xf
	v_cndmask_b32_e64 v57, v169, v36, s[20:21]
	v_max3_f32 v44, v44, v56, v57
	s_waitcnt lgkmcnt(1)
	v_add_f32_e32 v34, v34, v35
	s_nop 1
	v_mov_b32_dpp v35, v34 quad_perm:[2,3,0,1] row_mask:0xf bank_mask:0xf
	s_waitcnt lgkmcnt(1)
	v_add_f32_e32 v42, v37, v42
	s_nop 1
	v_mov_b32_dpp v50, v42 row_mirror row_mask:0xf bank_mask:0xf
	s_waitcnt lgkmcnt(1)
	v_add_f32_e32 v52, v34, v35
	v_mov_b32_e32 v34, v83
	v_mov_b32_e32 v83, v85
	v_mov_b32_e32 v35, v84
	v_pk_mul_f32 v[36:37], v[82:83], v[146:147]
	s_nop 1
	v_mov_b32_dpp v53, v52 row_half_mirror row_mask:0xf bank_mask:0xf
	v_pk_fma_f32 v[34:35], v[34:35], v[148:149], v[36:37]
	s_waitcnt lgkmcnt(1)
	v_add_f32_e32 v36, v42, v50
	v_add_f32_e32 v34, v34, v35
	s_nop 1
	v_mov_b32_dpp v35, v34 quad_perm:[1,0,3,2] row_mask:0xf bank_mask:0xf
	s_waitcnt lgkmcnt(1)
	v_add_f32_e32 v42, v52, v53
	v_cndmask_b32_e64 v62, v169, v36, s[22:23]
	s_nop 1
	v_mov_b32_dpp v50, v42 row_mirror row_mask:0xf bank_mask:0xf
	s_waitcnt lgkmcnt(1)
; __device__ __forceinline__ void attn_sample_g12(const Args& a, LAS unsigned char* lds, const bf16* Q, const bf16* Kb, const bf16* Vb, bf16* OG, float* ML, int b, int g, int tid) {
;     ...
;         for (int jj = 0; jj < 16; ++jj) { float t = (kk[jj][0] * q[0] + kk[jj][1] * q[1]) + (kk[jj][2] * q[2] + kk[jj][3] * q[3]);
;             t += __shfl_xor(t, 1); t += __shfl_xor(t, 2); t += __shfl_xor(t, 4); t += __shfl_xor(t, 8);
;             sc[jj] = (j0 + jj < jend) ? t : -INFINITY; cm = fmaxf(cm, sc[jj]); }
	v_add_f32_e32 v52, v34, v35
	v_mov_b32_e32 v34, v91
	v_mov_b32_e32 v91, v93
	v_mov_b32_e32 v35, v92
	v_pk_mul_f32 v[36:37], v[90:91], v[146:147]
	s_nop 1
	v_mov_b32_dpp v53, v52 quad_perm:[2,3,0,1] row_mask:0xf bank_mask:0xf
	v_pk_fma_f32 v[34:35], v[34:35], v[148:149], v[36:37]
	s_waitcnt lgkmcnt(1)
	v_add_f32_e32 v36, v42, v50
	v_add_f32_e32 v34, v34, v35
	s_nop 1
	v_mov_b32_dpp v35, v34 quad_perm:[1,0,3,2] row_mask:0xf bank_mask:0xf
	s_waitcnt lgkmcnt(1)
	v_add_f32_e32 v42, v52, v53
	v_cndmask_b32_e64 v63, v169, v36, s[24:25]
	s_nop 1
	v_mov_b32_dpp v50, v42 row_half_mirror row_mask:0xf bank_mask:0xf
	v_max3_f32 v44, v44, v62, v63
	s_waitcnt lgkmcnt(1)
	v_add_f32_e32 v52, v34, v35
	v_mov_b32_e32 v34, v99
	v_mov_b32_e32 v99, v101
	v_mov_b32_e32 v35, v100
	v_pk_mul_f32 v[36:37], v[98:99], v[146:147]
	s_nop 1
	v_mov_b32_dpp v53, v52 quad_perm:[2,3,0,1] row_mask:0xf bank_mask:0xf
	v_pk_fma_f32 v[34:35], v[34:35], v[148:149], v[36:37]
	s_waitcnt lgkmcnt(1)
	v_add_f32_e32 v36, v42, v50
	v_add_f32_e32 v34, v34, v35
	s_nop 1
	v_mov_b32_dpp v35, v34 quad_perm:[1,0,3,2] row_mask:0xf bank_mask:0xf
	s_nop 1
	v_mov_b32_dpp v37, v36 row_mirror row_mask:0xf bank_mask:0xf
	s_waitcnt lgkmcnt(2)
	v_add_f32_e32 v42, v52, v53
	s_nop 1
	v_mov_b32_dpp v50, v42 row_half_mirror row_mask:0xf bank_mask:0xf
	s_waitcnt lgkmcnt(2)
	v_add_f32_e32 v34, v34, v35
	s_nop 1
	v_mov_b32_dpp v35, v34 quad_perm:[2,3,0,1] row_mask:0xf bank_mask:0xf
	s_waitcnt lgkmcnt(2)
	v_add_f32_e32 v52, v36, v37
	s_waitcnt lgkmcnt(1)
	v_add_f32_e32 v42, v42, v50
	s_nop 1
	v_mov_b32_dpp v50, v42 row_mirror row_mask:0xf bank_mask:0xf
	v_cndmask_b32_e64 v64, v169, v52, s[26:27]
	s_waitcnt lgkmcnt(1)
	v_add_f32_e32 v53, v34, v35
	v_mov_b32_e32 v34, v107
	v_mov_b32_e32 v107, v109
	v_mov_b32_e32 v35, v108
	v_pk_mul_f32 v[36:37], v[106:107], v[146:147]
	s_nop 1
	v_mov_b32_dpp v54, v53 row_half_mirror row_mask:0xf bank_mask:0xf
	v_pk_fma_f32 v[34:35], v[34:35], v[148:149], v[36:37]
	s_waitcnt lgkmcnt(1)
	v_add_f32_e32 v36, v42, v50
	v_add_f32_e32 v34, v34, v35
	s_nop 1
	v_mov_b32_dpp v35, v34 quad_perm:[1,0,3,2] row_mask:0xf bank_mask:0xf
	s_waitcnt lgkmcnt(1)
	v_add_f32_e32 v37, v53, v54
	s_nop 1
	v_mov_b32_dpp v42, v37 row_mirror row_mask:0xf bank_mask:0xf
	v_cndmask_b32_e64 v65, v169, v36, s[28:29]
	v_max3_f32 v44, v44, v64, v65
	s_waitcnt lgkmcnt(1)
	v_add_f32_e32 v34, v34, v35
	s_nop 1
	v_mov_b32_dpp v35, v34 quad_perm:[2,3,0,1] row_mask:0xf bank_mask:0xf
	s_waitcnt lgkmcnt(1)
	v_add_f32_e32 v36, v37, v42
	v_cndmask_b32_e64 v70, v169, v36, s[30:31]
	v_mov_b32_e32 v54, v6
	v_mov_b32_e32 v6, v10
	s_waitcnt lgkmcnt(0)
	v_add_f32_e32 v42, v34, v35
	v_mov_b32_e32 v34, v111
	v_mov_b32_e32 v111, v113
	v_mov_b32_e32 v35, v112
	v_pk_mul_f32 v[36:37], v[110:111], v[146:147]
	s_nop 1
	v_mov_b32_dpp v50, v42 row_half_mirror row_mask:0xf bank_mask:0xf
	v_pk_fma_f32 v[34:35], v[34:35], v[148:149], v[36:37]
	s_nop 0
	v_add_f32_e32 v52, v34, v35
	v_mov_b32_e32 v34, v115
	v_mov_b32_e32 v115, v117
	v_mov_b32_e32 v35, v116
	v_pk_mul_f32 v[36:37], v[114:115], v[146:147]
	s_nop 1
	v_mov_b32_dpp v53, v52 quad_perm:[1,0,3,2] row_mask:0xf bank_mask:0xf
	v_pk_fma_f32 v[34:35], v[34:35], v[148:149], v[36:37]
	s_waitcnt lgkmcnt(1)
	v_add_f32_e32 v36, v42, v50
	v_add_f32_e32 v34, v34, v35
	s_nop 1
	v_mov_b32_dpp v35, v34 quad_perm:[1,0,3,2] row_mask:0xf bank_mask:0xf
	s_nop 1
	v_mov_b32_dpp v37, v36 row_mirror row_mask:0xf bank_mask:0xf
	s_waitcnt lgkmcnt(2)
	v_add_f32_e32 v42, v52, v53
	s_nop 1
	v_mov_b32_dpp v50, v42 quad_perm:[2,3,0,1] row_mask:0xf bank_mask:0xf
	s_waitcnt lgkmcnt(2)
	v_add_f32_e32 v34, v34, v35
	s_nop 1
	v_mov_b32_dpp v35, v34 quad_perm:[2,3,0,1] row_mask:0xf bank_mask:0xf
	s_waitcnt lgkmcnt(2)
	v_add_f32_e32 v36, v36, v37
	v_cndmask_b32_e64 v71, v169, v36, s[34:35]
	s_waitcnt lgkmcnt(1)
	v_add_f32_e32 v42, v42, v50
	s_nop 1
	v_mov_b32_dpp v50, v42 row_half_mirror row_mask:0xf bank_mask:0xf
	s_waitcnt lgkmcnt(1)
	v_add_f32_e32 v52, v34, v35
	v_mov_b32_e32 v34, v119
	v_mov_b32_e32 v119, v121
	v_mov_b32_e32 v35, v120
	v_pk_mul_f32 v[36:37], v[118:119], v[146:147]
	s_nop 1
	v_mov_b32_dpp v53, v52 row_half_mirror row_mask:0xf bank_mask:0xf
	v_pk_fma_f32 v[34:35], v[34:35], v[148:149], v[36:37]
	s_waitcnt lgkmcnt(1)
	v_add_f32_e32 v36, v42, v50
	v_add_f32_e32 v34, v34, v35
	s_nop 1
	v_mov_b32_dpp v35, v34 quad_perm:[1,0,3,2] row_mask:0xf bank_mask:0xf
	s_waitcnt lgkmcnt(1)
	v_add_f32_e32 v42, v52, v53
	s_nop 1
	v_mov_b32_dpp v37, v36 row_mirror row_mask:0xf bank_mask:0xf
	s_nop 1
	v_mov_b32_dpp v50, v42 row_mirror row_mask:0xf bank_mask:0xf
	v_max3_f32 v44, v44, v70, v71
	s_waitcnt lgkmcnt(2)
	v_add_f32_e32 v34, v34, v35
	s_nop 1
	v_mov_b32_dpp v35, v34 quad_perm:[2,3,0,1] row_mask:0xf bank_mask:0xf
	s_waitcnt lgkmcnt(2)
	v_add_f32_e32 v36, v36, v37
	s_waitcnt lgkmcnt(1)
	v_add_f32_e32 v42, v42, v50
	v_cndmask_b32_e64 v72, v169, v36, s[36:37]
	v_cndmask_b32_e64 v73, v169, v42, s[38:39]
	s_waitcnt lgkmcnt(0)
	v_add_f32_e32 v50, v34, v35
	v_mov_b32_e32 v34, v123
	v_mov_b32_e32 v123, v125
	v_mov_b32_e32 v35, v124
	v_pk_mul_f32 v[36:37], v[122:123], v[146:147]
	v_max3_f32 v44, v44, v72, v73
	v_pk_fma_f32 v[34:35], v[34:35], v[148:149], v[36:37]
	s_nop 0
	v_add_f32_e32 v52, v34, v35
	v_mov_b32_e32 v34, v127
	v_mov_b32_e32 v127, v129
	v_mov_b32_e32 v35, v128
	v_pk_mul_f32 v[36:37], v[126:127], v[146:147]
	s_nop 1
	v_mov_b32_dpp v53, v52 quad_perm:[1,0,3,2] row_mask:0xf bank_mask:0xf
	v_pk_fma_f32 v[34:35], v[34:35], v[148:149], v[36:37]
	s_nop 1
	v_mov_b32_dpp v36, v50 row_half_mirror row_mask:0xf bank_mask:0xf
	v_add_f32_e32 v34, v34, v35
	s_nop 1
	v_mov_b32_dpp v35, v34 quad_perm:[1,0,3,2] row_mask:0xf bank_mask:0xf
	s_waitcnt lgkmcnt(2)
; __device__ __forceinline__ void attn_sample_g12(const Args& a, LAS unsigned char* lds, const bf16* Q, const bf16* Kb, const bf16* Vb, bf16* OG, float* ML, int b, int g, int tid) {
;     ...
;         for (int jj = 0; jj < 16; ++jj) { float t = (kk[jj][0] * q[0] + kk[jj][1] * q[1]) + (kk[jj][2] * q[2] + kk[jj][3] * q[3]);
;             t += __shfl_xor(t, 1); t += __shfl_xor(t, 2); t += __shfl_xor(t, 4); t += __shfl_xor(t, 8);
;             sc[jj] = (j0 + jj < jend) ? t : -INFINITY; cm = fmaxf(cm, sc[jj]); }
;         const float mn = fmaxf(m, cm), scale = __builtin_amdgcn_exp2f(m - mn);
;         l *= scale; o[0] *= scale; o[1] *= scale; o[2] *= scale; o[3] *= scale;
; #pragma unroll
;         for (int jj = 0; jj < 16; ++jj) { const float p = __builtin_amdgcn_exp2f(sc[jj] - mn); l += p; o[0] += p * vv[jj][0]; o[1] += p * vv[jj][1]; o[2] += p * vv[jj][2]; o[3] += p * vv[jj][3]; }
;         m = mn;
;     }
	v_add_f32_e32 v37, v52, v53
	s_nop 1
	v_mov_b32_dpp v52, v37 quad_perm:[2,3,0,1] row_mask:0xf bank_mask:0xf
	s_waitcnt lgkmcnt(2)
	v_add_f32_e32 v36, v50, v36
	s_nop 1
	v_mov_b32_dpp v50, v36 row_mirror row_mask:0xf bank_mask:0xf
	s_waitcnt lgkmcnt(2)
	v_add_f32_e32 v34, v34, v35
	s_nop 1
	v_mov_b32_dpp v35, v34 quad_perm:[2,3,0,1] row_mask:0xf bank_mask:0xf
	s_waitcnt lgkmcnt(2)
	v_add_f32_e32 v37, v37, v52
	s_nop 1
	v_mov_b32_dpp v42, v37 row_half_mirror row_mask:0xf bank_mask:0xf
	s_waitcnt lgkmcnt(2)
	v_add_f32_e32 v36, v36, v50
	v_cndmask_b32_e64 v78, v169, v36, s[40:41]
	s_waitcnt lgkmcnt(1)
	v_add_f32_e32 v34, v34, v35
	s_nop 1
	v_mov_b32_dpp v35, v34 row_half_mirror row_mask:0xf bank_mask:0xf
	s_waitcnt lgkmcnt(1)
	v_add_f32_e32 v37, v37, v42
	s_nop 1
	v_mov_b32_dpp v42, v37 row_mirror row_mask:0xf bank_mask:0xf
	v_mov_b32_e32 v53, v4
	v_mov_b32_e32 v4, v3
	s_waitcnt lgkmcnt(1)
	v_add_f32_e32 v34, v34, v35
	s_nop 1
	v_mov_b32_dpp v35, v34 row_mirror row_mask:0xf bank_mask:0xf
	s_waitcnt lgkmcnt(1)
	v_add_f32_e32 v36, v37, v42
	v_cndmask_b32_e64 v37, v169, v36, s[42:43]
	v_max3_f32 v36, v44, v78, v37
	v_mov_b32_e32 v52, v2
	s_waitcnt lgkmcnt(0)
	v_add_f32_e32 v34, v34, v35
	v_cndmask_b32_e64 v35, v169, v34, s[44:45]
	v_max3_f32 v34, v176, v36, v35
	v_sub_f32_e32 v36, v176, v34
	v_sub_f32_e32 v42, v43, v34
	v_exp_f32_e32 v36, v36
	v_exp_f32_e32 v42, v42
	v_sub_f32_e32 v43, v45, v34
	v_exp_f32_e32 v44, v43
	v_sub_f32_e32 v43, v51, v34
	v_exp_f32_e32 v50, v43
	v_fma_f32 v43, v154, v36, v42
	v_add_f32_e32 v43, v44, v43
	v_sub_f32_e32 v7, v57, v34
	v_add_f32_e32 v43, v50, v43
	v_pk_mul_f32 v[2:3], v[4:5], v[42:43] op_sel_hi:[1,0]
	v_sub_f32_e32 v4, v56, v34
	v_pk_fma_f32 v[2:3], v[150:151], v[36:37], v[2:3] op_sel_hi:[1,0,1]
	v_exp_f32_e32 v4, v4
	v_pk_mul_f32 v[52:53], v[52:53], v[42:43] op_sel_hi:[1,0]
	v_pk_fma_f32 v[2:3], v[8:9], v[44:45], v[2:3] op_sel_hi:[1,0,1]
	v_exp_f32_e32 v8, v7
	v_sub_f32_e32 v7, v62, v34
	v_pk_fma_f32 v[52:53], v[152:153], v[36:37], v[52:53] op_sel_hi:[1,0,1]
	v_exp_f32_e32 v10, v7
	v_sub_f32_e32 v9, v63, v34
	v_pk_fma_f32 v[52:53], v[54:55], v[44:45], v[52:53] op_sel_hi:[1,0,1]
	v_mov_b32_e32 v54, v14
	v_mov_b32_e32 v55, v16
	v_mov_b32_e32 v16, v15
	v_exp_f32_e32 v14, v9
	v_sub_f32_e32 v9, v64, v34
	v_pk_fma_f32 v[2:3], v[16:17], v[50:51], v[2:3] op_sel_hi:[1,0,1]
	v_add_f32_e32 v5, v4, v43
	v_exp_f32_e32 v16, v9
	v_sub_f32_e32 v9, v65, v34
	v_add_f32_e32 v5, v8, v5
	v_exp_f32_e32 v36, v9
	v_sub_f32_e32 v9, v70, v34
	v_add_f32_e32 v5, v10, v5
	v_exp_f32_e32 v42, v9
	v_sub_f32_e32 v9, v71, v34
	v_add_f32_e32 v5, v14, v5
	v_exp_f32_e32 v44, v9
	v_sub_f32_e32 v9, v72, v34
	v_pk_fma_f32 v[52:53], v[54:55], v[50:51], v[52:53] op_sel_hi:[1,0,1]
	v_add_f32_e32 v5, v16, v5
	v_exp_f32_e32 v50, v9
	v_sub_f32_e32 v9, v73, v34
	v_add_f32_e32 v5, v36, v5
	v_exp_f32_e32 v54, v9
	v_sub_f32_e32 v9, v78, v34
	v_add_f32_e32 v5, v42, v5
	v_exp_f32_e32 v56, v9
	v_add_f32_e32 v5, v44, v5
	v_add_f32_e32 v5, v50, v5
	v_add_f32_e32 v5, v54, v5
	v_mov_b32_e32 v7, v12
	v_mov_b32_e32 v12, v11
	v_add_f32_e32 v5, v56, v5
	v_pk_fma_f32 v[6:7], v[6:7], v[4:5], v[52:53] op_sel_hi:[1,0,1]
	v_mov_b32_e32 v52, v18
	v_mov_b32_e32 v53, v20
	v_pk_fma_f32 v[2:3], v[12:13], v[4:5], v[2:3] op_sel_hi:[1,0,1]
	v_mov_b32_e32 v20, v19
	v_pk_fma_f32 v[6:7], v[52:53], v[8:9], v[6:7] op_sel_hi:[1,0,1]
	v_mov_b32_e32 v52, v22
	v_mov_b32_e32 v53, v24
	v_pk_fma_f32 v[2:3], v[20:21], v[8:9], v[2:3] op_sel_hi:[1,0,1]
	v_mov_b32_e32 v24, v23
	v_pk_fma_f32 v[6:7], v[52:53], v[10:11], v[6:7] op_sel_hi:[1,0,1]
	v_mov_b32_e32 v52, v26
	v_mov_b32_e32 v53, v28
	v_pk_fma_f32 v[2:3], v[24:25], v[10:11], v[2:3] op_sel_hi:[1,0,1]
	v_mov_b32_e32 v28, v27
	v_pk_fma_f32 v[6:7], v[52:53], v[14:15], v[6:7] op_sel_hi:[1,0,1]
	v_mov_b32_e32 v52, v30
	v_mov_b32_e32 v53, v32
	v_pk_fma_f32 v[2:3], v[28:29], v[14:15], v[2:3] op_sel_hi:[1,0,1]
	v_mov_b32_e32 v32, v31
	v_pk_fma_f32 v[6:7], v[52:53], v[16:17], v[6:7] op_sel_hi:[1,0,1]
	v_mov_b32_e32 v52, v38
	v_mov_b32_e32 v53, v40
	v_pk_fma_f32 v[2:3], v[32:33], v[16:17], v[2:3] op_sel_hi:[1,0,1]
	v_mov_b32_e32 v40, v39
	v_pk_fma_f32 v[6:7], v[52:53], v[36:37], v[6:7] op_sel_hi:[1,0,1]
	v_mov_b32_e32 v52, v46
	v_mov_b32_e32 v53, v48
	v_pk_fma_f32 v[2:3], v[40:41], v[36:37], v[2:3] op_sel_hi:[1,0,1]
	v_mov_b32_e32 v48, v47
	v_sub_f32_e32 v4, v37, v34
	v_pk_fma_f32 v[6:7], v[52:53], v[42:43], v[6:7] op_sel_hi:[1,0,1]
	v_mov_b32_e32 v52, v58
	v_mov_b32_e32 v53, v60
	v_pk_fma_f32 v[2:3], v[48:49], v[42:43], v[2:3] op_sel_hi:[1,0,1]
	v_mov_b32_e32 v60, v59
	v_exp_f32_e32 v4, v4
	v_sub_f32_e32 v8, v35, v34
	v_pk_fma_f32 v[6:7], v[52:53], v[44:45], v[6:7] op_sel_hi:[1,0,1]
	v_mov_b32_e32 v52, v66
	v_mov_b32_e32 v53, v68
	v_pk_fma_f32 v[2:3], v[60:61], v[44:45], v[2:3] op_sel_hi:[1,0,1]
	v_mov_b32_e32 v68, v67
	v_exp_f32_e32 v8, v8
	v_pk_fma_f32 v[6:7], v[52:53], v[50:51], v[6:7] op_sel_hi:[1,0,1]
	v_mov_b32_e32 v52, v74
	v_mov_b32_e32 v53, v76
	v_pk_fma_f32 v[2:3], v[68:69], v[50:51], v[2:3] op_sel_hi:[1,0,1]
	v_mov_b32_e32 v76, v75
	v_pk_fma_f32 v[6:7], v[52:53], v[54:55], v[6:7] op_sel_hi:[1,0,1]
	v_mov_b32_e32 v52, v86
	v_mov_b32_e32 v53, v88
	v_pk_fma_f32 v[2:3], v[76:77], v[54:55], v[2:3] op_sel_hi:[1,0,1]
	v_mov_b32_e32 v88, v87
	v_pk_fma_f32 v[6:7], v[52:53], v[56:57], v[6:7] op_sel_hi:[1,0,1]
	v_pk_fma_f32 v[2:3], v[88:89], v[56:57], v[2:3] op_sel_hi:[1,0,1]
	v_add_f32_e32 v5, v4, v5
	v_mov_b32_e32 v10, v94
	v_mov_b32_e32 v11, v96
	v_mov_b32_e32 v96, v95
	v_add_f32_e32 v154, v8, v5
	v_pk_fma_f32 v[6:7], v[10:11], v[4:5], v[6:7] op_sel_hi:[1,0,1]
	v_pk_fma_f32 v[2:3], v[96:97], v[4:5], v[2:3] op_sel_hi:[1,0,1]
	v_mov_b32_e32 v4, v102
	v_mov_b32_e32 v5, v104
	v_pk_fma_f32 v[152:153], v[4:5], v[8:9], v[6:7] op_sel_hi:[1,0,1]
	v_add_u32_e32 v6, 1, v132
	v_mov_b32_e32 v104, v103
	v_cmp_ge_u32_e32 vcc, v6, v158
	v_pk_fma_f32 v[150:151], v[104:105], v[8:9], v[2:3] op_sel_hi:[1,0,1]
	s_or_b64 s[48:49], vcc, s[48:49]
	v_mov_b32_e32 v176, v34
	s_andn2_b64 exec, exec, s[48:49]
	s_cbranch_execz .LBB0_1087
